# residual-update (EpiRes) epilogue of the out/down GEMMs rewritten by hand: all 16 tile loads issued up front with counted vmcnt waits, stores after, batched lane reductions
# baseline (speedup 1.0000x reference)
.LBB0_978:
	v_and_b32_e32 v178, 15, v219
	v_bfe_u32 v179, v219, 4, 2
	v_bfe_u32 v180, v219, 6, 2
	v_bfe_u32 v181, v219, 8, 1
	v_lshl_or_b32 v226, v181, 6, v178
	s_lshl_b32 s30, s52, 8
	v_or_b32_e32 v226, s30, v226
	v_lshlrev_b32_e32 v216, 12, v226
	v_lshlrev_b32_e32 v217, 7, v226
	v_lshlrev_b32_e32 v227, 6, v180
	v_lshl_or_b32 v227, v179, 4, v227
	s_lshl_b32 s30, s42, 9
	v_add3_u32 v216, v216, s30, v227
	s_lshl_b32 s30, s42, 4
	v_lshlrev_b32_e32 v227, 2, v180
	v_add3_u32 v217, v217, s30, v227
	v_and_b32_e32 v228, 63, v219
	v_xor_b32_e32 v229, 32, v228
	v_xor_b32_e32 v228, 16, v228
	v_lshlrev_b32_e32 v228, 2, v228
	v_lshlrev_b32_e32 v229, 2, v229
	global_load_dwordx4 v[132:135], v216, s[16:17]
	global_load_dwordx4 v[136:139], v216, s[16:17] offset:256
	v_add_u32_e32 v227, 0x10000, v216
	global_load_dwordx4 v[140:143], v227, s[16:17]
	global_load_dwordx4 v[144:147], v227, s[16:17] offset:256
	v_add_u32_e32 v226, 0x20000, v216
	global_load_dwordx4 v[148:151], v226, s[16:17]
	global_load_dwordx4 v[152:155], v226, s[16:17] offset:256
	v_add_u32_e32 v227, 0x30000, v216
	global_load_dwordx4 v[156:159], v227, s[16:17]
	global_load_dwordx4 v[188:191], v227, s[16:17] offset:256
	v_add_u32_e32 v226, 0x80000, v216
	global_load_dwordx4 v[192:195], v226, s[16:17]
	global_load_dwordx4 v[196:199], v226, s[16:17] offset:256
	v_add_u32_e32 v227, 0x90000, v216
	global_load_dwordx4 v[200:203], v227, s[16:17]
	global_load_dwordx4 v[204:207], v227, s[16:17] offset:256
	v_add_u32_e32 v226, 0xa0000, v216
	global_load_dwordx4 v[208:211], v226, s[16:17]
	global_load_dwordx4 v[212:215], v226, s[16:17] offset:256
	v_add_u32_e32 v227, 0xb0000, v216
	global_load_dwordx4 v[170:173], v227, s[16:17]
	global_load_dwordx4 v[174:177], v227, s[16:17] offset:256
	s_waitcnt vmcnt(14)
	v_lshlrev_b32_e32 v178, 16, v132
	v_and_b32_e32 v179, 0xffff0000, v132
	v_add_f32_e32 v128, v128, v178
	v_add_f32_e32 v129, v129, v179
	v_lshlrev_b32_e32 v180, 16, v133
	v_and_b32_e32 v181, 0xffff0000, v133
	v_add_f32_e32 v130, v130, v180
	v_add_f32_e32 v131, v131, v181
	v_lshlrev_b32_e32 v178, 16, v134
	v_and_b32_e32 v179, 0xffff0000, v134
	v_add_f32_e32 v124, v124, v178
	v_add_f32_e32 v125, v125, v179
	v_lshlrev_b32_e32 v180, 16, v135
	v_and_b32_e32 v181, 0xffff0000, v135
	v_add_f32_e32 v126, v126, v180
	v_add_f32_e32 v127, v127, v181
	v_cvt_pk_bf16_f32 v132, v128, v129
	v_cvt_pk_bf16_f32 v133, v130, v131
	v_cvt_pk_bf16_f32 v134, v124, v125
	v_cvt_pk_bf16_f32 v135, v126, v127
	v_mul_f32_e32 v178, v129, v129
	v_mul_f32_e32 v179, v131, v131
	v_mul_f32_e32 v180, v125, v125
	v_mul_f32_e32 v181, v127, v127
	v_fmac_f32_e32 v178, v128, v128
	v_fmac_f32_e32 v179, v130, v130
	v_fmac_f32_e32 v180, v124, v124
	v_fmac_f32_e32 v181, v126, v126
	v_add_f32_e32 v178, v178, v179
	v_add_f32_e32 v180, v180, v181
	v_add_f32_e32 v128, v178, v180
	v_lshlrev_b32_e32 v178, 16, v136
	v_and_b32_e32 v179, 0xffff0000, v136
	v_add_f32_e32 v120, v120, v178
	v_add_f32_e32 v121, v121, v179
	v_lshlrev_b32_e32 v180, 16, v137
	v_and_b32_e32 v181, 0xffff0000, v137
	v_add_f32_e32 v122, v122, v180
	v_add_f32_e32 v123, v123, v181
	v_lshlrev_b32_e32 v178, 16, v138
	v_and_b32_e32 v179, 0xffff0000, v138
	v_add_f32_e32 v116, v116, v178
	v_add_f32_e32 v117, v117, v179
	v_lshlrev_b32_e32 v180, 16, v139
	v_and_b32_e32 v181, 0xffff0000, v139
	v_add_f32_e32 v118, v118, v180
	v_add_f32_e32 v119, v119, v181
	v_cvt_pk_bf16_f32 v136, v120, v121
	v_cvt_pk_bf16_f32 v137, v122, v123
	v_cvt_pk_bf16_f32 v138, v116, v117
	v_cvt_pk_bf16_f32 v139, v118, v119
	v_mul_f32_e32 v178, v121, v121
	v_mul_f32_e32 v179, v123, v123
	v_mul_f32_e32 v180, v117, v117
	v_mul_f32_e32 v181, v119, v119
	v_fmac_f32_e32 v178, v120, v120
	v_fmac_f32_e32 v179, v122, v122
	v_fmac_f32_e32 v180, v116, v116
	v_fmac_f32_e32 v181, v118, v118
	v_add_f32_e32 v178, v178, v179
	v_add_f32_e32 v180, v180, v181
	v_add_f32_e32 v120, v178, v180
	global_store_dwordx4 v216, v[132:135], s[16:17]
	global_store_dwordx4 v216, v[136:139], s[16:17] offset:256
	v_add_f32_e32 v128, v128, v120
	s_waitcnt vmcnt(14)
	v_lshlrev_b32_e32 v178, 16, v140
	v_and_b32_e32 v179, 0xffff0000, v140
	v_add_f32_e32 v112, v112, v178
	v_add_f32_e32 v113, v113, v179
	v_lshlrev_b32_e32 v180, 16, v141
	v_and_b32_e32 v181, 0xffff0000, v141
	v_add_f32_e32 v114, v114, v180
	v_add_f32_e32 v115, v115, v181
	v_lshlrev_b32_e32 v178, 16, v142
	v_and_b32_e32 v179, 0xffff0000, v142
	v_add_f32_e32 v108, v108, v178
	v_add_f32_e32 v109, v109, v179
	v_lshlrev_b32_e32 v180, 16, v143
	v_and_b32_e32 v181, 0xffff0000, v143
	v_add_f32_e32 v110, v110, v180
	v_add_f32_e32 v111, v111, v181
	v_cvt_pk_bf16_f32 v140, v112, v113
	v_cvt_pk_bf16_f32 v141, v114, v115
	v_cvt_pk_bf16_f32 v142, v108, v109
	v_cvt_pk_bf16_f32 v143, v110, v111
	v_mul_f32_e32 v178, v113, v113
	v_mul_f32_e32 v179, v115, v115
	v_mul_f32_e32 v180, v109, v109
	v_mul_f32_e32 v181, v111, v111
	v_fmac_f32_e32 v178, v112, v112
	v_fmac_f32_e32 v179, v114, v114
	v_fmac_f32_e32 v180, v108, v108
	v_fmac_f32_e32 v181, v110, v110
	v_add_f32_e32 v178, v178, v179
	v_add_f32_e32 v180, v180, v181
	v_add_f32_e32 v112, v178, v180
	v_lshlrev_b32_e32 v178, 16, v144
	v_and_b32_e32 v179, 0xffff0000, v144
	v_add_f32_e32 v104, v104, v178
	v_add_f32_e32 v105, v105, v179
	v_lshlrev_b32_e32 v180, 16, v145
	v_and_b32_e32 v181, 0xffff0000, v145
	v_add_f32_e32 v106, v106, v180
	v_add_f32_e32 v107, v107, v181
	v_lshlrev_b32_e32 v178, 16, v146
	v_and_b32_e32 v179, 0xffff0000, v146
	v_add_f32_e32 v100, v100, v178
	v_add_f32_e32 v101, v101, v179
	v_lshlrev_b32_e32 v180, 16, v147
	v_and_b32_e32 v181, 0xffff0000, v147
	v_add_f32_e32 v102, v102, v180
	v_add_f32_e32 v103, v103, v181
	v_cvt_pk_bf16_f32 v144, v104, v105
	v_cvt_pk_bf16_f32 v145, v106, v107
	v_cvt_pk_bf16_f32 v146, v100, v101
	v_cvt_pk_bf16_f32 v147, v102, v103
	v_mul_f32_e32 v178, v105, v105
	v_mul_f32_e32 v179, v107, v107
	v_mul_f32_e32 v180, v101, v101
	v_mul_f32_e32 v181, v103, v103
	v_fmac_f32_e32 v178, v104, v104
	v_fmac_f32_e32 v179, v106, v106
	v_fmac_f32_e32 v180, v100, v100
	v_fmac_f32_e32 v181, v102, v102
	v_add_f32_e32 v178, v178, v179
	v_add_f32_e32 v180, v180, v181
	v_add_f32_e32 v104, v178, v180
	v_add_u32_e32 v227, 0x10000, v216
	global_store_dwordx4 v227, v[140:143], s[16:17]
	global_store_dwordx4 v227, v[144:147], s[16:17] offset:256
	v_add_f32_e32 v112, v112, v104
	s_waitcnt vmcnt(14)
	v_lshlrev_b32_e32 v178, 16, v148
	v_and_b32_e32 v179, 0xffff0000, v148
	v_add_f32_e32 v96, v96, v178
	v_add_f32_e32 v97, v97, v179
	v_lshlrev_b32_e32 v180, 16, v149
	v_and_b32_e32 v181, 0xffff0000, v149
	v_add_f32_e32 v98, v98, v180
	v_add_f32_e32 v99, v99, v181
	v_lshlrev_b32_e32 v178, 16, v150
	v_and_b32_e32 v179, 0xffff0000, v150
	v_add_f32_e32 v92, v92, v178
	v_add_f32_e32 v93, v93, v179
	v_lshlrev_b32_e32 v180, 16, v151
	v_and_b32_e32 v181, 0xffff0000, v151
	v_add_f32_e32 v94, v94, v180
	v_add_f32_e32 v95, v95, v181
	v_cvt_pk_bf16_f32 v148, v96, v97
	v_cvt_pk_bf16_f32 v149, v98, v99
	v_cvt_pk_bf16_f32 v150, v92, v93
	v_cvt_pk_bf16_f32 v151, v94, v95
	v_mul_f32_e32 v178, v97, v97
	v_mul_f32_e32 v179, v99, v99
	v_mul_f32_e32 v180, v93, v93
	v_mul_f32_e32 v181, v95, v95
	v_fmac_f32_e32 v178, v96, v96
	v_fmac_f32_e32 v179, v98, v98
	v_fmac_f32_e32 v180, v92, v92
	v_fmac_f32_e32 v181, v94, v94
	v_add_f32_e32 v178, v178, v179
	v_add_f32_e32 v180, v180, v181
	v_add_f32_e32 v96, v178, v180
	v_lshlrev_b32_e32 v178, 16, v152
	v_and_b32_e32 v179, 0xffff0000, v152
	v_add_f32_e32 v88, v88, v178
	v_add_f32_e32 v89, v89, v179
	v_lshlrev_b32_e32 v180, 16, v153
	v_and_b32_e32 v181, 0xffff0000, v153
	v_add_f32_e32 v90, v90, v180
	v_add_f32_e32 v91, v91, v181
	v_lshlrev_b32_e32 v178, 16, v154
	v_and_b32_e32 v179, 0xffff0000, v154
	v_add_f32_e32 v84, v84, v178
	v_add_f32_e32 v85, v85, v179
	v_lshlrev_b32_e32 v180, 16, v155
	v_and_b32_e32 v181, 0xffff0000, v155
	v_add_f32_e32 v86, v86, v180
	v_add_f32_e32 v87, v87, v181
	v_cvt_pk_bf16_f32 v152, v88, v89
	v_cvt_pk_bf16_f32 v153, v90, v91
	v_cvt_pk_bf16_f32 v154, v84, v85
	v_cvt_pk_bf16_f32 v155, v86, v87
	v_mul_f32_e32 v178, v89, v89
	v_mul_f32_e32 v179, v91, v91
	v_mul_f32_e32 v180, v85, v85
	v_mul_f32_e32 v181, v87, v87
	v_fmac_f32_e32 v178, v88, v88
	v_fmac_f32_e32 v179, v90, v90
	v_fmac_f32_e32 v180, v84, v84
	v_fmac_f32_e32 v181, v86, v86
	v_add_f32_e32 v178, v178, v179
	v_add_f32_e32 v180, v180, v181
	v_add_f32_e32 v88, v178, v180
	v_add_u32_e32 v226, 0x20000, v216
	global_store_dwordx4 v226, v[148:151], s[16:17]
	global_store_dwordx4 v226, v[152:155], s[16:17] offset:256
	v_add_f32_e32 v96, v96, v88
	s_waitcnt vmcnt(14)
	v_lshlrev_b32_e32 v178, 16, v156
	v_and_b32_e32 v179, 0xffff0000, v156
	v_add_f32_e32 v80, v80, v178
	v_add_f32_e32 v81, v81, v179
	v_lshlrev_b32_e32 v180, 16, v157
	v_and_b32_e32 v181, 0xffff0000, v157
	v_add_f32_e32 v82, v82, v180
	v_add_f32_e32 v83, v83, v181
	v_lshlrev_b32_e32 v178, 16, v158
	v_and_b32_e32 v179, 0xffff0000, v158
	v_add_f32_e32 v76, v76, v178
	v_add_f32_e32 v77, v77, v179
	v_lshlrev_b32_e32 v180, 16, v159
	v_and_b32_e32 v181, 0xffff0000, v159
	v_add_f32_e32 v78, v78, v180
	v_add_f32_e32 v79, v79, v181
	v_cvt_pk_bf16_f32 v156, v80, v81
	v_cvt_pk_bf16_f32 v157, v82, v83
	v_cvt_pk_bf16_f32 v158, v76, v77
	v_cvt_pk_bf16_f32 v159, v78, v79
	v_mul_f32_e32 v178, v81, v81
	v_mul_f32_e32 v179, v83, v83
	v_mul_f32_e32 v180, v77, v77
	v_mul_f32_e32 v181, v79, v79
	v_fmac_f32_e32 v178, v80, v80
	v_fmac_f32_e32 v179, v82, v82
	v_fmac_f32_e32 v180, v76, v76
	v_fmac_f32_e32 v181, v78, v78
	v_add_f32_e32 v178, v178, v179
	v_add_f32_e32 v180, v180, v181
	v_add_f32_e32 v80, v178, v180
	v_lshlrev_b32_e32 v178, 16, v188
	v_and_b32_e32 v179, 0xffff0000, v188
	v_add_f32_e32 v72, v72, v178
	v_add_f32_e32 v73, v73, v179
	v_lshlrev_b32_e32 v180, 16, v189
	v_and_b32_e32 v181, 0xffff0000, v189
	v_add_f32_e32 v74, v74, v180
	v_add_f32_e32 v75, v75, v181
	v_lshlrev_b32_e32 v178, 16, v190
	v_and_b32_e32 v179, 0xffff0000, v190
	v_add_f32_e32 v68, v68, v178
	v_add_f32_e32 v69, v69, v179
	v_lshlrev_b32_e32 v180, 16, v191
	v_and_b32_e32 v181, 0xffff0000, v191
	v_add_f32_e32 v70, v70, v180
	v_add_f32_e32 v71, v71, v181
	v_cvt_pk_bf16_f32 v188, v72, v73
	v_cvt_pk_bf16_f32 v189, v74, v75
	v_cvt_pk_bf16_f32 v190, v68, v69
	v_cvt_pk_bf16_f32 v191, v70, v71
	v_mul_f32_e32 v178, v73, v73
	v_mul_f32_e32 v179, v75, v75
	v_mul_f32_e32 v180, v69, v69
	v_mul_f32_e32 v181, v71, v71
	v_fmac_f32_e32 v178, v72, v72
	v_fmac_f32_e32 v179, v74, v74
	v_fmac_f32_e32 v180, v68, v68
	v_fmac_f32_e32 v181, v70, v70
	v_add_f32_e32 v178, v178, v179
	v_add_f32_e32 v180, v180, v181
	v_add_f32_e32 v72, v178, v180
	v_add_u32_e32 v227, 0x30000, v216
	global_store_dwordx4 v227, v[156:159], s[16:17]
	global_store_dwordx4 v227, v[188:191], s[16:17] offset:256
	v_add_f32_e32 v80, v80, v72
	s_waitcnt vmcnt(14)
	v_lshlrev_b32_e32 v178, 16, v192
	v_and_b32_e32 v179, 0xffff0000, v192
	v_add_f32_e32 v64, v64, v178
	v_add_f32_e32 v65, v65, v179
	v_lshlrev_b32_e32 v180, 16, v193
	v_and_b32_e32 v181, 0xffff0000, v193
	v_add_f32_e32 v66, v66, v180
	v_add_f32_e32 v67, v67, v181
	v_lshlrev_b32_e32 v178, 16, v194
	v_and_b32_e32 v179, 0xffff0000, v194
	v_add_f32_e32 v60, v60, v178
	v_add_f32_e32 v61, v61, v179
	v_lshlrev_b32_e32 v180, 16, v195
	v_and_b32_e32 v181, 0xffff0000, v195
	v_add_f32_e32 v62, v62, v180
	v_add_f32_e32 v63, v63, v181
	v_cvt_pk_bf16_f32 v192, v64, v65
	v_cvt_pk_bf16_f32 v193, v66, v67
	v_cvt_pk_bf16_f32 v194, v60, v61
	v_cvt_pk_bf16_f32 v195, v62, v63
	v_mul_f32_e32 v178, v65, v65
	v_mul_f32_e32 v179, v67, v67
	v_mul_f32_e32 v180, v61, v61
	v_mul_f32_e32 v181, v63, v63
	v_fmac_f32_e32 v178, v64, v64
	v_fmac_f32_e32 v179, v66, v66
	v_fmac_f32_e32 v180, v60, v60
	v_fmac_f32_e32 v181, v62, v62
	v_add_f32_e32 v178, v178, v179
	v_add_f32_e32 v180, v180, v181
	v_add_f32_e32 v64, v178, v180
	v_lshlrev_b32_e32 v178, 16, v196
	v_and_b32_e32 v179, 0xffff0000, v196
	v_add_f32_e32 v56, v56, v178
	v_add_f32_e32 v57, v57, v179
	v_lshlrev_b32_e32 v180, 16, v197
	v_and_b32_e32 v181, 0xffff0000, v197
	v_add_f32_e32 v58, v58, v180
	v_add_f32_e32 v59, v59, v181
	v_lshlrev_b32_e32 v178, 16, v198
	v_and_b32_e32 v179, 0xffff0000, v198
	v_add_f32_e32 v52, v52, v178
	v_add_f32_e32 v53, v53, v179
	v_lshlrev_b32_e32 v180, 16, v199
	v_and_b32_e32 v181, 0xffff0000, v199
	v_add_f32_e32 v54, v54, v180
	v_add_f32_e32 v55, v55, v181
	v_cvt_pk_bf16_f32 v196, v56, v57
	v_cvt_pk_bf16_f32 v197, v58, v59
	v_cvt_pk_bf16_f32 v198, v52, v53
	v_cvt_pk_bf16_f32 v199, v54, v55
	v_mul_f32_e32 v178, v57, v57
	v_mul_f32_e32 v179, v59, v59
	v_mul_f32_e32 v180, v53, v53
	v_mul_f32_e32 v181, v55, v55
	v_fmac_f32_e32 v178, v56, v56
	v_fmac_f32_e32 v179, v58, v58
	v_fmac_f32_e32 v180, v52, v52
	v_fmac_f32_e32 v181, v54, v54
	v_add_f32_e32 v178, v178, v179
	v_add_f32_e32 v180, v180, v181
	v_add_f32_e32 v56, v178, v180
	v_add_u32_e32 v226, 0x80000, v216
	global_store_dwordx4 v226, v[192:195], s[16:17]
	global_store_dwordx4 v226, v[196:199], s[16:17] offset:256
	v_add_f32_e32 v64, v64, v56
	s_waitcnt vmcnt(14)
	v_lshlrev_b32_e32 v178, 16, v200
	v_and_b32_e32 v179, 0xffff0000, v200
	v_add_f32_e32 v48, v48, v178
	v_add_f32_e32 v49, v49, v179
	v_lshlrev_b32_e32 v180, 16, v201
	v_and_b32_e32 v181, 0xffff0000, v201
	v_add_f32_e32 v50, v50, v180
	v_add_f32_e32 v51, v51, v181
	v_lshlrev_b32_e32 v178, 16, v202
	v_and_b32_e32 v179, 0xffff0000, v202
	v_add_f32_e32 v44, v44, v178
	v_add_f32_e32 v45, v45, v179
	v_lshlrev_b32_e32 v180, 16, v203
	v_and_b32_e32 v181, 0xffff0000, v203
	v_add_f32_e32 v46, v46, v180
	v_add_f32_e32 v47, v47, v181
	v_cvt_pk_bf16_f32 v200, v48, v49
	v_cvt_pk_bf16_f32 v201, v50, v51
	v_cvt_pk_bf16_f32 v202, v44, v45
	v_cvt_pk_bf16_f32 v203, v46, v47
	v_mul_f32_e32 v178, v49, v49
	v_mul_f32_e32 v179, v51, v51
	v_mul_f32_e32 v180, v45, v45
	v_mul_f32_e32 v181, v47, v47
	v_fmac_f32_e32 v178, v48, v48
	v_fmac_f32_e32 v179, v50, v50
	v_fmac_f32_e32 v180, v44, v44
	v_fmac_f32_e32 v181, v46, v46
	v_add_f32_e32 v178, v178, v179
	v_add_f32_e32 v180, v180, v181
	v_add_f32_e32 v48, v178, v180
	v_lshlrev_b32_e32 v178, 16, v204
	v_and_b32_e32 v179, 0xffff0000, v204
	v_add_f32_e32 v40, v40, v178
	v_add_f32_e32 v41, v41, v179
	v_lshlrev_b32_e32 v180, 16, v205
	v_and_b32_e32 v181, 0xffff0000, v205
	v_add_f32_e32 v42, v42, v180
	v_add_f32_e32 v43, v43, v181
	v_lshlrev_b32_e32 v178, 16, v206
	v_and_b32_e32 v179, 0xffff0000, v206
	v_add_f32_e32 v36, v36, v178
	v_add_f32_e32 v37, v37, v179
	v_lshlrev_b32_e32 v180, 16, v207
	v_and_b32_e32 v181, 0xffff0000, v207
	v_add_f32_e32 v38, v38, v180
	v_add_f32_e32 v39, v39, v181
	v_cvt_pk_bf16_f32 v204, v40, v41
	v_cvt_pk_bf16_f32 v205, v42, v43
	v_cvt_pk_bf16_f32 v206, v36, v37
	v_cvt_pk_bf16_f32 v207, v38, v39
	v_mul_f32_e32 v178, v41, v41
	v_mul_f32_e32 v179, v43, v43
	v_mul_f32_e32 v180, v37, v37
	v_mul_f32_e32 v181, v39, v39
	v_fmac_f32_e32 v178, v40, v40
	v_fmac_f32_e32 v179, v42, v42
	v_fmac_f32_e32 v180, v36, v36
	v_fmac_f32_e32 v181, v38, v38
	v_add_f32_e32 v178, v178, v179
	v_add_f32_e32 v180, v180, v181
	v_add_f32_e32 v40, v178, v180
	v_add_u32_e32 v227, 0x90000, v216
	global_store_dwordx4 v227, v[200:203], s[16:17]
	global_store_dwordx4 v227, v[204:207], s[16:17] offset:256
	v_add_f32_e32 v48, v48, v40
	s_waitcnt vmcnt(14)
	v_lshlrev_b32_e32 v178, 16, v208
	v_and_b32_e32 v179, 0xffff0000, v208
	v_add_f32_e32 v32, v32, v178
	v_add_f32_e32 v33, v33, v179
	v_lshlrev_b32_e32 v180, 16, v209
	v_and_b32_e32 v181, 0xffff0000, v209
	v_add_f32_e32 v34, v34, v180
	v_add_f32_e32 v35, v35, v181
	v_lshlrev_b32_e32 v178, 16, v210
	v_and_b32_e32 v179, 0xffff0000, v210
	v_add_f32_e32 v28, v28, v178
	v_add_f32_e32 v29, v29, v179
	v_lshlrev_b32_e32 v180, 16, v211
	v_and_b32_e32 v181, 0xffff0000, v211
	v_add_f32_e32 v30, v30, v180
	v_add_f32_e32 v31, v31, v181
	v_cvt_pk_bf16_f32 v208, v32, v33
	v_cvt_pk_bf16_f32 v209, v34, v35
	v_cvt_pk_bf16_f32 v210, v28, v29
	v_cvt_pk_bf16_f32 v211, v30, v31
	v_mul_f32_e32 v178, v33, v33
	v_mul_f32_e32 v179, v35, v35
	v_mul_f32_e32 v180, v29, v29
	v_mul_f32_e32 v181, v31, v31
	v_fmac_f32_e32 v178, v32, v32
	v_fmac_f32_e32 v179, v34, v34
	v_fmac_f32_e32 v180, v28, v28
	v_fmac_f32_e32 v181, v30, v30
	v_add_f32_e32 v178, v178, v179
	v_add_f32_e32 v180, v180, v181
	v_add_f32_e32 v32, v178, v180
	v_lshlrev_b32_e32 v178, 16, v212
	v_and_b32_e32 v179, 0xffff0000, v212
	v_add_f32_e32 v24, v24, v178
	v_add_f32_e32 v25, v25, v179
	v_lshlrev_b32_e32 v180, 16, v213
	v_and_b32_e32 v181, 0xffff0000, v213
	v_add_f32_e32 v26, v26, v180
	v_add_f32_e32 v27, v27, v181
	v_lshlrev_b32_e32 v178, 16, v214
	v_and_b32_e32 v179, 0xffff0000, v214
	v_add_f32_e32 v20, v20, v178
	v_add_f32_e32 v21, v21, v179
	v_lshlrev_b32_e32 v180, 16, v215
	v_and_b32_e32 v181, 0xffff0000, v215
	v_add_f32_e32 v22, v22, v180
	v_add_f32_e32 v23, v23, v181
	v_cvt_pk_bf16_f32 v212, v24, v25
	v_cvt_pk_bf16_f32 v213, v26, v27
	v_cvt_pk_bf16_f32 v214, v20, v21
	v_cvt_pk_bf16_f32 v215, v22, v23
	v_mul_f32_e32 v178, v25, v25
	v_mul_f32_e32 v179, v27, v27
	v_mul_f32_e32 v180, v21, v21
	v_mul_f32_e32 v181, v23, v23
	v_fmac_f32_e32 v178, v24, v24
	v_fmac_f32_e32 v179, v26, v26
	v_fmac_f32_e32 v180, v20, v20
	v_fmac_f32_e32 v181, v22, v22
	v_add_f32_e32 v178, v178, v179
	v_add_f32_e32 v180, v180, v181
	v_add_f32_e32 v24, v178, v180
	v_add_u32_e32 v226, 0xa0000, v216
	global_store_dwordx4 v226, v[208:211], s[16:17]
	global_store_dwordx4 v226, v[212:215], s[16:17] offset:256
	v_add_f32_e32 v32, v32, v24
	s_waitcnt vmcnt(14)
	v_lshlrev_b32_e32 v178, 16, v170
	v_and_b32_e32 v179, 0xffff0000, v170
	v_add_f32_e32 v16, v16, v178
	v_add_f32_e32 v17, v17, v179
	v_lshlrev_b32_e32 v180, 16, v171
	v_and_b32_e32 v181, 0xffff0000, v171
	v_add_f32_e32 v18, v18, v180
	v_add_f32_e32 v19, v19, v181
	v_lshlrev_b32_e32 v178, 16, v172
	v_and_b32_e32 v179, 0xffff0000, v172
	v_add_f32_e32 v12, v12, v178
	v_add_f32_e32 v13, v13, v179
	v_lshlrev_b32_e32 v180, 16, v173
	v_and_b32_e32 v181, 0xffff0000, v173
	v_add_f32_e32 v14, v14, v180
	v_add_f32_e32 v15, v15, v181
	v_cvt_pk_bf16_f32 v170, v16, v17
	v_cvt_pk_bf16_f32 v171, v18, v19
	v_cvt_pk_bf16_f32 v172, v12, v13
	v_cvt_pk_bf16_f32 v173, v14, v15
	v_mul_f32_e32 v178, v17, v17
	v_mul_f32_e32 v179, v19, v19
	v_mul_f32_e32 v180, v13, v13
	v_mul_f32_e32 v181, v15, v15
	v_fmac_f32_e32 v178, v16, v16
	v_fmac_f32_e32 v179, v18, v18
	v_fmac_f32_e32 v180, v12, v12
	v_fmac_f32_e32 v181, v14, v14
	v_add_f32_e32 v178, v178, v179
	v_add_f32_e32 v180, v180, v181
	v_add_f32_e32 v16, v178, v180
	v_lshlrev_b32_e32 v178, 16, v174
	v_and_b32_e32 v179, 0xffff0000, v174
	v_add_f32_e32 v8, v8, v178
	v_add_f32_e32 v9, v9, v179
	v_lshlrev_b32_e32 v180, 16, v175
	v_and_b32_e32 v181, 0xffff0000, v175
	v_add_f32_e32 v10, v10, v180
	v_add_f32_e32 v11, v11, v181
	v_lshlrev_b32_e32 v178, 16, v176
	v_and_b32_e32 v179, 0xffff0000, v176
	v_add_f32_e32 v4, v4, v178
	v_add_f32_e32 v5, v5, v179
	v_lshlrev_b32_e32 v180, 16, v177
	v_and_b32_e32 v181, 0xffff0000, v177
	v_add_f32_e32 v6, v6, v180
	v_add_f32_e32 v7, v7, v181
	v_cvt_pk_bf16_f32 v174, v8, v9
	v_cvt_pk_bf16_f32 v175, v10, v11
	v_cvt_pk_bf16_f32 v176, v4, v5
	v_cvt_pk_bf16_f32 v177, v6, v7
	v_mul_f32_e32 v178, v9, v9
	v_mul_f32_e32 v179, v11, v11
	v_mul_f32_e32 v180, v5, v5
	v_mul_f32_e32 v181, v7, v7
	v_fmac_f32_e32 v178, v8, v8
	v_fmac_f32_e32 v179, v10, v10
	v_fmac_f32_e32 v180, v4, v4
	v_fmac_f32_e32 v181, v6, v6
	v_add_f32_e32 v178, v178, v179
	v_add_f32_e32 v180, v180, v181
	v_add_f32_e32 v8, v178, v180
	v_add_u32_e32 v227, 0xb0000, v216
	global_store_dwordx4 v227, v[170:173], s[16:17]
	global_store_dwordx4 v227, v[174:177], s[16:17] offset:256
	v_add_f32_e32 v16, v16, v8
	ds_bpermute_b32 v129, v228, v128
	ds_bpermute_b32 v113, v228, v112
	ds_bpermute_b32 v97, v228, v96
	ds_bpermute_b32 v81, v228, v80
	ds_bpermute_b32 v65, v228, v64
	ds_bpermute_b32 v49, v228, v48
	ds_bpermute_b32 v33, v228, v32
	ds_bpermute_b32 v17, v228, v16
	s_waitcnt lgkmcnt(0)
	v_add_f32_e32 v128, v128, v129
	v_add_f32_e32 v112, v112, v113
	v_add_f32_e32 v96, v96, v97
	v_add_f32_e32 v80, v80, v81
	v_add_f32_e32 v64, v64, v65
	v_add_f32_e32 v48, v48, v49
	v_add_f32_e32 v32, v32, v33
	v_add_f32_e32 v16, v16, v17
	s_nop 0
	ds_bpermute_b32 v129, v229, v128
	ds_bpermute_b32 v113, v229, v112
	ds_bpermute_b32 v97, v229, v96
	ds_bpermute_b32 v81, v229, v80
	ds_bpermute_b32 v65, v229, v64
	ds_bpermute_b32 v49, v229, v48
	ds_bpermute_b32 v33, v229, v32
	ds_bpermute_b32 v17, v229, v16
	s_waitcnt lgkmcnt(0)
	v_add_f32_e32 v128, v128, v129
	v_add_f32_e32 v112, v112, v113
	v_add_f32_e32 v96, v96, v97
	v_add_f32_e32 v80, v80, v81
	v_add_f32_e32 v64, v64, v65
	v_add_f32_e32 v48, v48, v49
	v_add_f32_e32 v32, v32, v33
	v_add_f32_e32 v16, v16, v17
	s_mov_b64 exec, 0xffff
	global_store_dword v217, v128, s[18:19]
	v_add_u32_e32 v227, 0x800, v217
	global_store_dword v227, v112, s[18:19]
	v_add_u32_e32 v226, 0x1000, v217
	global_store_dword v226, v96, s[18:19]
	v_add_u32_e32 v227, 0x1800, v217
	global_store_dword v227, v80, s[18:19]
	v_add_u32_e32 v226, 0x4000, v217
	global_store_dword v226, v64, s[18:19]
	v_add_u32_e32 v227, 0x4800, v217
	global_store_dword v227, v48, s[18:19]
	v_add_u32_e32 v226, 0x5000, v217
	global_store_dword v226, v32, s[18:19]
	v_add_u32_e32 v227, 0x5800, v217
	global_store_dword v227, v16, s[18:19]
	s_mov_b64 exec, -1
	s_andn2_b64 vcc, exec, s[8:9]
	s_mov_b64 s[8:9], -1
	s_cbranch_vccnz .LBB0_967
	s_andn2_b64 vcc, exec, s[12:13]
	s_cbranch_vccnz .LBB0_966
	s_barrier
	s_branch .LBB0_966

.LBB0_1208:
	v_and_b32_e32 v178, 15, v219
	v_bfe_u32 v179, v219, 4, 2
	v_bfe_u32 v180, v219, 6, 2
	v_bfe_u32 v181, v219, 8, 1
	v_lshl_or_b32 v226, v181, 6, v178
	s_lshl_b32 s22, s51, 8
	v_or_b32_e32 v226, s22, v226
	v_lshlrev_b32_e32 v216, 12, v226
	v_lshlrev_b32_e32 v217, 7, v226
	v_lshlrev_b32_e32 v227, 6, v180
	v_lshl_or_b32 v227, v179, 4, v227
	s_lshl_b32 s22, s42, 9
	v_add3_u32 v216, v216, s22, v227
	s_lshl_b32 s22, s42, 4
	v_lshlrev_b32_e32 v227, 2, v180
	v_add3_u32 v217, v217, s22, v227
	v_and_b32_e32 v228, 63, v219
	v_xor_b32_e32 v229, 32, v228
	v_xor_b32_e32 v228, 16, v228
	v_lshlrev_b32_e32 v228, 2, v228
	v_lshlrev_b32_e32 v229, 2, v229
	global_load_dwordx4 v[132:135], v216, s[12:13]
	global_load_dwordx4 v[136:139], v216, s[12:13] offset:256
	v_add_u32_e32 v227, 0x10000, v216
	global_load_dwordx4 v[140:143], v227, s[12:13]
	global_load_dwordx4 v[144:147], v227, s[12:13] offset:256
	v_add_u32_e32 v226, 0x20000, v216
	global_load_dwordx4 v[148:151], v226, s[12:13]
	global_load_dwordx4 v[152:155], v226, s[12:13] offset:256
	v_add_u32_e32 v227, 0x30000, v216
	global_load_dwordx4 v[156:159], v227, s[12:13]
	global_load_dwordx4 v[188:191], v227, s[12:13] offset:256
	v_add_u32_e32 v226, 0x80000, v216
	global_load_dwordx4 v[192:195], v226, s[12:13]
	global_load_dwordx4 v[196:199], v226, s[12:13] offset:256
	v_add_u32_e32 v227, 0x90000, v216
	global_load_dwordx4 v[200:203], v227, s[12:13]
	global_load_dwordx4 v[204:207], v227, s[12:13] offset:256
	v_add_u32_e32 v226, 0xa0000, v216
	global_load_dwordx4 v[208:211], v226, s[12:13]
	global_load_dwordx4 v[212:215], v226, s[12:13] offset:256
	v_add_u32_e32 v227, 0xb0000, v216
	global_load_dwordx4 v[170:173], v227, s[12:13]
	global_load_dwordx4 v[174:177], v227, s[12:13] offset:256
	s_waitcnt vmcnt(14)
	v_lshlrev_b32_e32 v178, 16, v132
	v_and_b32_e32 v179, 0xffff0000, v132
	v_add_f32_e32 v128, v128, v178
	v_add_f32_e32 v129, v129, v179
	v_lshlrev_b32_e32 v180, 16, v133
	v_and_b32_e32 v181, 0xffff0000, v133
	v_add_f32_e32 v130, v130, v180
	v_add_f32_e32 v131, v131, v181
	v_lshlrev_b32_e32 v178, 16, v134
	v_and_b32_e32 v179, 0xffff0000, v134
	v_add_f32_e32 v124, v124, v178
	v_add_f32_e32 v125, v125, v179
	v_lshlrev_b32_e32 v180, 16, v135
	v_and_b32_e32 v181, 0xffff0000, v135
	v_add_f32_e32 v126, v126, v180
	v_add_f32_e32 v127, v127, v181
	v_cvt_pk_bf16_f32 v132, v128, v129
	v_cvt_pk_bf16_f32 v133, v130, v131
	v_cvt_pk_bf16_f32 v134, v124, v125
	v_cvt_pk_bf16_f32 v135, v126, v127
	v_mul_f32_e32 v178, v129, v129
	v_mul_f32_e32 v179, v131, v131
	v_mul_f32_e32 v180, v125, v125
	v_mul_f32_e32 v181, v127, v127
	v_fmac_f32_e32 v178, v128, v128
	v_fmac_f32_e32 v179, v130, v130
	v_fmac_f32_e32 v180, v124, v124
	v_fmac_f32_e32 v181, v126, v126
	v_add_f32_e32 v178, v178, v179
	v_add_f32_e32 v180, v180, v181
	v_add_f32_e32 v128, v178, v180
	v_lshlrev_b32_e32 v178, 16, v136
	v_and_b32_e32 v179, 0xffff0000, v136
	v_add_f32_e32 v120, v120, v178
	v_add_f32_e32 v121, v121, v179
	v_lshlrev_b32_e32 v180, 16, v137
	v_and_b32_e32 v181, 0xffff0000, v137
	v_add_f32_e32 v122, v122, v180
	v_add_f32_e32 v123, v123, v181
	v_lshlrev_b32_e32 v178, 16, v138
	v_and_b32_e32 v179, 0xffff0000, v138
	v_add_f32_e32 v116, v116, v178
	v_add_f32_e32 v117, v117, v179
	v_lshlrev_b32_e32 v180, 16, v139
	v_and_b32_e32 v181, 0xffff0000, v139
	v_add_f32_e32 v118, v118, v180
	v_add_f32_e32 v119, v119, v181
	v_cvt_pk_bf16_f32 v136, v120, v121
	v_cvt_pk_bf16_f32 v137, v122, v123
	v_cvt_pk_bf16_f32 v138, v116, v117
	v_cvt_pk_bf16_f32 v139, v118, v119
	v_mul_f32_e32 v178, v121, v121
	v_mul_f32_e32 v179, v123, v123
	v_mul_f32_e32 v180, v117, v117
	v_mul_f32_e32 v181, v119, v119
	v_fmac_f32_e32 v178, v120, v120
	v_fmac_f32_e32 v179, v122, v122
	v_fmac_f32_e32 v180, v116, v116
	v_fmac_f32_e32 v181, v118, v118
	v_add_f32_e32 v178, v178, v179
	v_add_f32_e32 v180, v180, v181
	v_add_f32_e32 v120, v178, v180
	global_store_dwordx4 v216, v[132:135], s[12:13]
	global_store_dwordx4 v216, v[136:139], s[12:13] offset:256
	v_add_f32_e32 v128, v128, v120
	s_waitcnt vmcnt(14)
	v_lshlrev_b32_e32 v178, 16, v140
	v_and_b32_e32 v179, 0xffff0000, v140
	v_add_f32_e32 v112, v112, v178
	v_add_f32_e32 v113, v113, v179
	v_lshlrev_b32_e32 v180, 16, v141
	v_and_b32_e32 v181, 0xffff0000, v141
	v_add_f32_e32 v114, v114, v180
	v_add_f32_e32 v115, v115, v181
	v_lshlrev_b32_e32 v178, 16, v142
	v_and_b32_e32 v179, 0xffff0000, v142
	v_add_f32_e32 v108, v108, v178
	v_add_f32_e32 v109, v109, v179
	v_lshlrev_b32_e32 v180, 16, v143
	v_and_b32_e32 v181, 0xffff0000, v143
	v_add_f32_e32 v110, v110, v180
	v_add_f32_e32 v111, v111, v181
	v_cvt_pk_bf16_f32 v140, v112, v113
	v_cvt_pk_bf16_f32 v141, v114, v115
	v_cvt_pk_bf16_f32 v142, v108, v109
	v_cvt_pk_bf16_f32 v143, v110, v111
	v_mul_f32_e32 v178, v113, v113
	v_mul_f32_e32 v179, v115, v115
	v_mul_f32_e32 v180, v109, v109
	v_mul_f32_e32 v181, v111, v111
	v_fmac_f32_e32 v178, v112, v112
	v_fmac_f32_e32 v179, v114, v114
	v_fmac_f32_e32 v180, v108, v108
	v_fmac_f32_e32 v181, v110, v110
	v_add_f32_e32 v178, v178, v179
	v_add_f32_e32 v180, v180, v181
	v_add_f32_e32 v112, v178, v180
	v_lshlrev_b32_e32 v178, 16, v144
	v_and_b32_e32 v179, 0xffff0000, v144
	v_add_f32_e32 v104, v104, v178
	v_add_f32_e32 v105, v105, v179
	v_lshlrev_b32_e32 v180, 16, v145
	v_and_b32_e32 v181, 0xffff0000, v145
	v_add_f32_e32 v106, v106, v180
	v_add_f32_e32 v107, v107, v181
	v_lshlrev_b32_e32 v178, 16, v146
	v_and_b32_e32 v179, 0xffff0000, v146
	v_add_f32_e32 v100, v100, v178
	v_add_f32_e32 v101, v101, v179
	v_lshlrev_b32_e32 v180, 16, v147
	v_and_b32_e32 v181, 0xffff0000, v147
	v_add_f32_e32 v102, v102, v180
	v_add_f32_e32 v103, v103, v181
	v_cvt_pk_bf16_f32 v144, v104, v105
	v_cvt_pk_bf16_f32 v145, v106, v107
	v_cvt_pk_bf16_f32 v146, v100, v101
	v_cvt_pk_bf16_f32 v147, v102, v103
	v_mul_f32_e32 v178, v105, v105
	v_mul_f32_e32 v179, v107, v107
	v_mul_f32_e32 v180, v101, v101
	v_mul_f32_e32 v181, v103, v103
	v_fmac_f32_e32 v178, v104, v104
	v_fmac_f32_e32 v179, v106, v106
	v_fmac_f32_e32 v180, v100, v100
	v_fmac_f32_e32 v181, v102, v102
	v_add_f32_e32 v178, v178, v179
	v_add_f32_e32 v180, v180, v181
	v_add_f32_e32 v104, v178, v180
	v_add_u32_e32 v227, 0x10000, v216
	global_store_dwordx4 v227, v[140:143], s[12:13]
	global_store_dwordx4 v227, v[144:147], s[12:13] offset:256
	v_add_f32_e32 v112, v112, v104
	s_waitcnt vmcnt(14)
	v_lshlrev_b32_e32 v178, 16, v148
	v_and_b32_e32 v179, 0xffff0000, v148
	v_add_f32_e32 v96, v96, v178
	v_add_f32_e32 v97, v97, v179
	v_lshlrev_b32_e32 v180, 16, v149
	v_and_b32_e32 v181, 0xffff0000, v149
	v_add_f32_e32 v98, v98, v180
	v_add_f32_e32 v99, v99, v181
	v_lshlrev_b32_e32 v178, 16, v150
	v_and_b32_e32 v179, 0xffff0000, v150
	v_add_f32_e32 v92, v92, v178
	v_add_f32_e32 v93, v93, v179
	v_lshlrev_b32_e32 v180, 16, v151
	v_and_b32_e32 v181, 0xffff0000, v151
	v_add_f32_e32 v94, v94, v180
	v_add_f32_e32 v95, v95, v181
	v_cvt_pk_bf16_f32 v148, v96, v97
	v_cvt_pk_bf16_f32 v149, v98, v99
	v_cvt_pk_bf16_f32 v150, v92, v93
	v_cvt_pk_bf16_f32 v151, v94, v95
	v_mul_f32_e32 v178, v97, v97
	v_mul_f32_e32 v179, v99, v99
	v_mul_f32_e32 v180, v93, v93
	v_mul_f32_e32 v181, v95, v95
	v_fmac_f32_e32 v178, v96, v96
	v_fmac_f32_e32 v179, v98, v98
	v_fmac_f32_e32 v180, v92, v92
	v_fmac_f32_e32 v181, v94, v94
	v_add_f32_e32 v178, v178, v179
	v_add_f32_e32 v180, v180, v181
	v_add_f32_e32 v96, v178, v180
	v_lshlrev_b32_e32 v178, 16, v152
	v_and_b32_e32 v179, 0xffff0000, v152
	v_add_f32_e32 v88, v88, v178
	v_add_f32_e32 v89, v89, v179
	v_lshlrev_b32_e32 v180, 16, v153
	v_and_b32_e32 v181, 0xffff0000, v153
	v_add_f32_e32 v90, v90, v180
	v_add_f32_e32 v91, v91, v181
	v_lshlrev_b32_e32 v178, 16, v154
	v_and_b32_e32 v179, 0xffff0000, v154
	v_add_f32_e32 v84, v84, v178
	v_add_f32_e32 v85, v85, v179
	v_lshlrev_b32_e32 v180, 16, v155
	v_and_b32_e32 v181, 0xffff0000, v155
	v_add_f32_e32 v86, v86, v180
	v_add_f32_e32 v87, v87, v181
	v_cvt_pk_bf16_f32 v152, v88, v89
	v_cvt_pk_bf16_f32 v153, v90, v91
	v_cvt_pk_bf16_f32 v154, v84, v85
	v_cvt_pk_bf16_f32 v155, v86, v87
	v_mul_f32_e32 v178, v89, v89
	v_mul_f32_e32 v179, v91, v91
	v_mul_f32_e32 v180, v85, v85
	v_mul_f32_e32 v181, v87, v87
	v_fmac_f32_e32 v178, v88, v88
	v_fmac_f32_e32 v179, v90, v90
	v_fmac_f32_e32 v180, v84, v84
	v_fmac_f32_e32 v181, v86, v86
	v_add_f32_e32 v178, v178, v179
	v_add_f32_e32 v180, v180, v181
	v_add_f32_e32 v88, v178, v180
	v_add_u32_e32 v226, 0x20000, v216
	global_store_dwordx4 v226, v[148:151], s[12:13]
	global_store_dwordx4 v226, v[152:155], s[12:13] offset:256
	v_add_f32_e32 v96, v96, v88
	s_waitcnt vmcnt(14)
	v_lshlrev_b32_e32 v178, 16, v156
	v_and_b32_e32 v179, 0xffff0000, v156
	v_add_f32_e32 v80, v80, v178
	v_add_f32_e32 v81, v81, v179
	v_lshlrev_b32_e32 v180, 16, v157
	v_and_b32_e32 v181, 0xffff0000, v157
	v_add_f32_e32 v82, v82, v180
	v_add_f32_e32 v83, v83, v181
	v_lshlrev_b32_e32 v178, 16, v158
	v_and_b32_e32 v179, 0xffff0000, v158
	v_add_f32_e32 v76, v76, v178
	v_add_f32_e32 v77, v77, v179
	v_lshlrev_b32_e32 v180, 16, v159
	v_and_b32_e32 v181, 0xffff0000, v159
	v_add_f32_e32 v78, v78, v180
	v_add_f32_e32 v79, v79, v181
	v_cvt_pk_bf16_f32 v156, v80, v81
	v_cvt_pk_bf16_f32 v157, v82, v83
	v_cvt_pk_bf16_f32 v158, v76, v77
	v_cvt_pk_bf16_f32 v159, v78, v79
	v_mul_f32_e32 v178, v81, v81
	v_mul_f32_e32 v179, v83, v83
	v_mul_f32_e32 v180, v77, v77
	v_mul_f32_e32 v181, v79, v79
	v_fmac_f32_e32 v178, v80, v80
	v_fmac_f32_e32 v179, v82, v82
	v_fmac_f32_e32 v180, v76, v76
	v_fmac_f32_e32 v181, v78, v78
	v_add_f32_e32 v178, v178, v179
	v_add_f32_e32 v180, v180, v181
	v_add_f32_e32 v80, v178, v180
	v_lshlrev_b32_e32 v178, 16, v188
	v_and_b32_e32 v179, 0xffff0000, v188
	v_add_f32_e32 v72, v72, v178
	v_add_f32_e32 v73, v73, v179
	v_lshlrev_b32_e32 v180, 16, v189
	v_and_b32_e32 v181, 0xffff0000, v189
	v_add_f32_e32 v74, v74, v180
	v_add_f32_e32 v75, v75, v181
	v_lshlrev_b32_e32 v178, 16, v190
	v_and_b32_e32 v179, 0xffff0000, v190
	v_add_f32_e32 v68, v68, v178
	v_add_f32_e32 v69, v69, v179
	v_lshlrev_b32_e32 v180, 16, v191
	v_and_b32_e32 v181, 0xffff0000, v191
	v_add_f32_e32 v70, v70, v180
	v_add_f32_e32 v71, v71, v181
	v_cvt_pk_bf16_f32 v188, v72, v73
	v_cvt_pk_bf16_f32 v189, v74, v75
	v_cvt_pk_bf16_f32 v190, v68, v69
	v_cvt_pk_bf16_f32 v191, v70, v71
	v_mul_f32_e32 v178, v73, v73
	v_mul_f32_e32 v179, v75, v75
	v_mul_f32_e32 v180, v69, v69
	v_mul_f32_e32 v181, v71, v71
	v_fmac_f32_e32 v178, v72, v72
	v_fmac_f32_e32 v179, v74, v74
	v_fmac_f32_e32 v180, v68, v68
	v_fmac_f32_e32 v181, v70, v70
	v_add_f32_e32 v178, v178, v179
	v_add_f32_e32 v180, v180, v181
	v_add_f32_e32 v72, v178, v180
	v_add_u32_e32 v227, 0x30000, v216
	global_store_dwordx4 v227, v[156:159], s[12:13]
	global_store_dwordx4 v227, v[188:191], s[12:13] offset:256
	v_add_f32_e32 v80, v80, v72
	s_waitcnt vmcnt(14)
	v_lshlrev_b32_e32 v178, 16, v192
	v_and_b32_e32 v179, 0xffff0000, v192
	v_add_f32_e32 v64, v64, v178
	v_add_f32_e32 v65, v65, v179
	v_lshlrev_b32_e32 v180, 16, v193
	v_and_b32_e32 v181, 0xffff0000, v193
	v_add_f32_e32 v66, v66, v180
	v_add_f32_e32 v67, v67, v181
	v_lshlrev_b32_e32 v178, 16, v194
	v_and_b32_e32 v179, 0xffff0000, v194
	v_add_f32_e32 v60, v60, v178
	v_add_f32_e32 v61, v61, v179
	v_lshlrev_b32_e32 v180, 16, v195
	v_and_b32_e32 v181, 0xffff0000, v195
	v_add_f32_e32 v62, v62, v180
	v_add_f32_e32 v63, v63, v181
	v_cvt_pk_bf16_f32 v192, v64, v65
	v_cvt_pk_bf16_f32 v193, v66, v67
	v_cvt_pk_bf16_f32 v194, v60, v61
	v_cvt_pk_bf16_f32 v195, v62, v63
	v_mul_f32_e32 v178, v65, v65
	v_mul_f32_e32 v179, v67, v67
	v_mul_f32_e32 v180, v61, v61
	v_mul_f32_e32 v181, v63, v63
	v_fmac_f32_e32 v178, v64, v64
	v_fmac_f32_e32 v179, v66, v66
	v_fmac_f32_e32 v180, v60, v60
	v_fmac_f32_e32 v181, v62, v62
	v_add_f32_e32 v178, v178, v179
	v_add_f32_e32 v180, v180, v181
	v_add_f32_e32 v64, v178, v180
	v_lshlrev_b32_e32 v178, 16, v196
	v_and_b32_e32 v179, 0xffff0000, v196
	v_add_f32_e32 v56, v56, v178
	v_add_f32_e32 v57, v57, v179
	v_lshlrev_b32_e32 v180, 16, v197
	v_and_b32_e32 v181, 0xffff0000, v197
	v_add_f32_e32 v58, v58, v180
	v_add_f32_e32 v59, v59, v181
	v_lshlrev_b32_e32 v178, 16, v198
	v_and_b32_e32 v179, 0xffff0000, v198
	v_add_f32_e32 v52, v52, v178
	v_add_f32_e32 v53, v53, v179
	v_lshlrev_b32_e32 v180, 16, v199
	v_and_b32_e32 v181, 0xffff0000, v199
	v_add_f32_e32 v54, v54, v180
	v_add_f32_e32 v55, v55, v181
	v_cvt_pk_bf16_f32 v196, v56, v57
	v_cvt_pk_bf16_f32 v197, v58, v59
	v_cvt_pk_bf16_f32 v198, v52, v53
	v_cvt_pk_bf16_f32 v199, v54, v55
	v_mul_f32_e32 v178, v57, v57
	v_mul_f32_e32 v179, v59, v59
	v_mul_f32_e32 v180, v53, v53
	v_mul_f32_e32 v181, v55, v55
	v_fmac_f32_e32 v178, v56, v56
	v_fmac_f32_e32 v179, v58, v58
	v_fmac_f32_e32 v180, v52, v52
	v_fmac_f32_e32 v181, v54, v54
	v_add_f32_e32 v178, v178, v179
	v_add_f32_e32 v180, v180, v181
	v_add_f32_e32 v56, v178, v180
	v_add_u32_e32 v226, 0x80000, v216
	global_store_dwordx4 v226, v[192:195], s[12:13]
	global_store_dwordx4 v226, v[196:199], s[12:13] offset:256
	v_add_f32_e32 v64, v64, v56
	s_waitcnt vmcnt(14)
	v_lshlrev_b32_e32 v178, 16, v200
	v_and_b32_e32 v179, 0xffff0000, v200
	v_add_f32_e32 v48, v48, v178
	v_add_f32_e32 v49, v49, v179
	v_lshlrev_b32_e32 v180, 16, v201
	v_and_b32_e32 v181, 0xffff0000, v201
	v_add_f32_e32 v50, v50, v180
	v_add_f32_e32 v51, v51, v181
	v_lshlrev_b32_e32 v178, 16, v202
	v_and_b32_e32 v179, 0xffff0000, v202
	v_add_f32_e32 v44, v44, v178
	v_add_f32_e32 v45, v45, v179
	v_lshlrev_b32_e32 v180, 16, v203
	v_and_b32_e32 v181, 0xffff0000, v203
	v_add_f32_e32 v46, v46, v180
	v_add_f32_e32 v47, v47, v181
	v_cvt_pk_bf16_f32 v200, v48, v49
	v_cvt_pk_bf16_f32 v201, v50, v51
	v_cvt_pk_bf16_f32 v202, v44, v45
	v_cvt_pk_bf16_f32 v203, v46, v47
	v_mul_f32_e32 v178, v49, v49
	v_mul_f32_e32 v179, v51, v51
	v_mul_f32_e32 v180, v45, v45
	v_mul_f32_e32 v181, v47, v47
	v_fmac_f32_e32 v178, v48, v48
	v_fmac_f32_e32 v179, v50, v50
	v_fmac_f32_e32 v180, v44, v44
	v_fmac_f32_e32 v181, v46, v46
	v_add_f32_e32 v178, v178, v179
	v_add_f32_e32 v180, v180, v181
	v_add_f32_e32 v48, v178, v180
	v_lshlrev_b32_e32 v178, 16, v204
	v_and_b32_e32 v179, 0xffff0000, v204
	v_add_f32_e32 v40, v40, v178
	v_add_f32_e32 v41, v41, v179
	v_lshlrev_b32_e32 v180, 16, v205
	v_and_b32_e32 v181, 0xffff0000, v205
	v_add_f32_e32 v42, v42, v180
	v_add_f32_e32 v43, v43, v181
	v_lshlrev_b32_e32 v178, 16, v206
	v_and_b32_e32 v179, 0xffff0000, v206
	v_add_f32_e32 v36, v36, v178
	v_add_f32_e32 v37, v37, v179
	v_lshlrev_b32_e32 v180, 16, v207
	v_and_b32_e32 v181, 0xffff0000, v207
	v_add_f32_e32 v38, v38, v180
	v_add_f32_e32 v39, v39, v181
	v_cvt_pk_bf16_f32 v204, v40, v41
	v_cvt_pk_bf16_f32 v205, v42, v43
	v_cvt_pk_bf16_f32 v206, v36, v37
	v_cvt_pk_bf16_f32 v207, v38, v39
	v_mul_f32_e32 v178, v41, v41
	v_mul_f32_e32 v179, v43, v43
	v_mul_f32_e32 v180, v37, v37
	v_mul_f32_e32 v181, v39, v39
	v_fmac_f32_e32 v178, v40, v40
	v_fmac_f32_e32 v179, v42, v42
	v_fmac_f32_e32 v180, v36, v36
	v_fmac_f32_e32 v181, v38, v38
	v_add_f32_e32 v178, v178, v179
	v_add_f32_e32 v180, v180, v181
	v_add_f32_e32 v40, v178, v180
	v_add_u32_e32 v227, 0x90000, v216
	global_store_dwordx4 v227, v[200:203], s[12:13]
	global_store_dwordx4 v227, v[204:207], s[12:13] offset:256
	v_add_f32_e32 v48, v48, v40
	s_waitcnt vmcnt(14)
	v_lshlrev_b32_e32 v178, 16, v208
	v_and_b32_e32 v179, 0xffff0000, v208
	v_add_f32_e32 v32, v32, v178
	v_add_f32_e32 v33, v33, v179
	v_lshlrev_b32_e32 v180, 16, v209
	v_and_b32_e32 v181, 0xffff0000, v209
	v_add_f32_e32 v34, v34, v180
	v_add_f32_e32 v35, v35, v181
	v_lshlrev_b32_e32 v178, 16, v210
	v_and_b32_e32 v179, 0xffff0000, v210
	v_add_f32_e32 v28, v28, v178
	v_add_f32_e32 v29, v29, v179
	v_lshlrev_b32_e32 v180, 16, v211
	v_and_b32_e32 v181, 0xffff0000, v211
	v_add_f32_e32 v30, v30, v180
	v_add_f32_e32 v31, v31, v181
	v_cvt_pk_bf16_f32 v208, v32, v33
	v_cvt_pk_bf16_f32 v209, v34, v35
	v_cvt_pk_bf16_f32 v210, v28, v29
	v_cvt_pk_bf16_f32 v211, v30, v31
	v_mul_f32_e32 v178, v33, v33
	v_mul_f32_e32 v179, v35, v35
	v_mul_f32_e32 v180, v29, v29
	v_mul_f32_e32 v181, v31, v31
	v_fmac_f32_e32 v178, v32, v32
	v_fmac_f32_e32 v179, v34, v34
	v_fmac_f32_e32 v180, v28, v28
	v_fmac_f32_e32 v181, v30, v30
	v_add_f32_e32 v178, v178, v179
	v_add_f32_e32 v180, v180, v181
	v_add_f32_e32 v32, v178, v180
	v_lshlrev_b32_e32 v178, 16, v212
	v_and_b32_e32 v179, 0xffff0000, v212
	v_add_f32_e32 v24, v24, v178
	v_add_f32_e32 v25, v25, v179
	v_lshlrev_b32_e32 v180, 16, v213
	v_and_b32_e32 v181, 0xffff0000, v213
	v_add_f32_e32 v26, v26, v180
	v_add_f32_e32 v27, v27, v181
	v_lshlrev_b32_e32 v178, 16, v214
	v_and_b32_e32 v179, 0xffff0000, v214
	v_add_f32_e32 v20, v20, v178
	v_add_f32_e32 v21, v21, v179
	v_lshlrev_b32_e32 v180, 16, v215
	v_and_b32_e32 v181, 0xffff0000, v215
	v_add_f32_e32 v22, v22, v180
	v_add_f32_e32 v23, v23, v181
	v_cvt_pk_bf16_f32 v212, v24, v25
	v_cvt_pk_bf16_f32 v213, v26, v27
	v_cvt_pk_bf16_f32 v214, v20, v21
	v_cvt_pk_bf16_f32 v215, v22, v23
	v_mul_f32_e32 v178, v25, v25
	v_mul_f32_e32 v179, v27, v27
	v_mul_f32_e32 v180, v21, v21
	v_mul_f32_e32 v181, v23, v23
	v_fmac_f32_e32 v178, v24, v24
	v_fmac_f32_e32 v179, v26, v26
	v_fmac_f32_e32 v180, v20, v20
	v_fmac_f32_e32 v181, v22, v22
	v_add_f32_e32 v178, v178, v179
	v_add_f32_e32 v180, v180, v181
	v_add_f32_e32 v24, v178, v180
	v_add_u32_e32 v226, 0xa0000, v216
	global_store_dwordx4 v226, v[208:211], s[12:13]
	global_store_dwordx4 v226, v[212:215], s[12:13] offset:256
	v_add_f32_e32 v32, v32, v24
	s_waitcnt vmcnt(14)
	v_lshlrev_b32_e32 v178, 16, v170
	v_and_b32_e32 v179, 0xffff0000, v170
	v_add_f32_e32 v16, v16, v178
	v_add_f32_e32 v17, v17, v179
	v_lshlrev_b32_e32 v180, 16, v171
	v_and_b32_e32 v181, 0xffff0000, v171
	v_add_f32_e32 v18, v18, v180
	v_add_f32_e32 v19, v19, v181
	v_lshlrev_b32_e32 v178, 16, v172
	v_and_b32_e32 v179, 0xffff0000, v172
	v_add_f32_e32 v12, v12, v178
	v_add_f32_e32 v13, v13, v179
	v_lshlrev_b32_e32 v180, 16, v173
	v_and_b32_e32 v181, 0xffff0000, v173
	v_add_f32_e32 v14, v14, v180
	v_add_f32_e32 v15, v15, v181
	v_cvt_pk_bf16_f32 v170, v16, v17
	v_cvt_pk_bf16_f32 v171, v18, v19
	v_cvt_pk_bf16_f32 v172, v12, v13
	v_cvt_pk_bf16_f32 v173, v14, v15
	v_mul_f32_e32 v178, v17, v17
	v_mul_f32_e32 v179, v19, v19
	v_mul_f32_e32 v180, v13, v13
	v_mul_f32_e32 v181, v15, v15
	v_fmac_f32_e32 v178, v16, v16
	v_fmac_f32_e32 v179, v18, v18
	v_fmac_f32_e32 v180, v12, v12
	v_fmac_f32_e32 v181, v14, v14
	v_add_f32_e32 v178, v178, v179
	v_add_f32_e32 v180, v180, v181
	v_add_f32_e32 v16, v178, v180
	v_lshlrev_b32_e32 v178, 16, v174
	v_and_b32_e32 v179, 0xffff0000, v174
	v_add_f32_e32 v8, v8, v178
	v_add_f32_e32 v9, v9, v179
	v_lshlrev_b32_e32 v180, 16, v175
	v_and_b32_e32 v181, 0xffff0000, v175
	v_add_f32_e32 v10, v10, v180
	v_add_f32_e32 v11, v11, v181
	v_lshlrev_b32_e32 v178, 16, v176
	v_and_b32_e32 v179, 0xffff0000, v176
	v_add_f32_e32 v4, v4, v178
	v_add_f32_e32 v5, v5, v179
	v_lshlrev_b32_e32 v180, 16, v177
	v_and_b32_e32 v181, 0xffff0000, v177
	v_add_f32_e32 v6, v6, v180
	v_add_f32_e32 v7, v7, v181
	v_cvt_pk_bf16_f32 v174, v8, v9
	v_cvt_pk_bf16_f32 v175, v10, v11
	v_cvt_pk_bf16_f32 v176, v4, v5
	v_cvt_pk_bf16_f32 v177, v6, v7
	v_mul_f32_e32 v178, v9, v9
	v_mul_f32_e32 v179, v11, v11
	v_mul_f32_e32 v180, v5, v5
	v_mul_f32_e32 v181, v7, v7
	v_fmac_f32_e32 v178, v8, v8
	v_fmac_f32_e32 v179, v10, v10
	v_fmac_f32_e32 v180, v4, v4
	v_fmac_f32_e32 v181, v6, v6
	v_add_f32_e32 v178, v178, v179
	v_add_f32_e32 v180, v180, v181
	v_add_f32_e32 v8, v178, v180
	v_add_u32_e32 v227, 0xb0000, v216
	global_store_dwordx4 v227, v[170:173], s[12:13]
	global_store_dwordx4 v227, v[174:177], s[12:13] offset:256
	v_add_f32_e32 v16, v16, v8
	ds_bpermute_b32 v129, v228, v128
	ds_bpermute_b32 v113, v228, v112
	ds_bpermute_b32 v97, v228, v96
	ds_bpermute_b32 v81, v228, v80
	ds_bpermute_b32 v65, v228, v64
	ds_bpermute_b32 v49, v228, v48
	ds_bpermute_b32 v33, v228, v32
	ds_bpermute_b32 v17, v228, v16
	s_waitcnt lgkmcnt(0)
	v_add_f32_e32 v128, v128, v129
	v_add_f32_e32 v112, v112, v113
	v_add_f32_e32 v96, v96, v97
	v_add_f32_e32 v80, v80, v81
	v_add_f32_e32 v64, v64, v65
	v_add_f32_e32 v48, v48, v49
	v_add_f32_e32 v32, v32, v33
	v_add_f32_e32 v16, v16, v17
	s_nop 0
	ds_bpermute_b32 v129, v229, v128
	ds_bpermute_b32 v113, v229, v112
	ds_bpermute_b32 v97, v229, v96
	ds_bpermute_b32 v81, v229, v80
	ds_bpermute_b32 v65, v229, v64
	ds_bpermute_b32 v49, v229, v48
	ds_bpermute_b32 v33, v229, v32
	ds_bpermute_b32 v17, v229, v16
	s_waitcnt lgkmcnt(0)
	v_add_f32_e32 v128, v128, v129
	v_add_f32_e32 v112, v112, v113
	v_add_f32_e32 v96, v96, v97
	v_add_f32_e32 v80, v80, v81
	v_add_f32_e32 v64, v64, v65
	v_add_f32_e32 v48, v48, v49
	v_add_f32_e32 v32, v32, v33
	v_add_f32_e32 v16, v16, v17
	s_mov_b64 exec, 0xffff
	global_store_dword v217, v128, s[16:17]
	v_add_u32_e32 v227, 0x800, v217
	global_store_dword v227, v112, s[16:17]
	v_add_u32_e32 v226, 0x1000, v217
	global_store_dword v226, v96, s[16:17]
	v_add_u32_e32 v227, 0x1800, v217
	global_store_dword v227, v80, s[16:17]
	v_add_u32_e32 v226, 0x4000, v217
	global_store_dword v226, v64, s[16:17]
	v_add_u32_e32 v227, 0x4800, v217
	global_store_dword v227, v48, s[16:17]
	v_add_u32_e32 v226, 0x5000, v217
	global_store_dword v226, v32, s[16:17]
	v_add_u32_e32 v227, 0x5800, v217
	global_store_dword v227, v16, s[16:17]
	s_mov_b64 exec, -1
	s_and_b64 vcc, exec, s[6:7]
	s_mov_b64 s[6:7], -1
	s_cbranch_vccnz .LBB0_1193
	s_andn2_b64 vcc, exec, s[10:11]
	s_cbranch_vccnz .LBB0_1192
	s_barrier
	s_branch .LBB0_1192
